# in-proj epilogue: second row half's rowsq loads issued with the first half's (one latency per unit), no vmcnt waits in the second half
# baseline (speedup 1.0000x reference)
;     __device__ __forceinline__ void operator()(const f32x4 (&acc)[2][2][4][2], const Unit& u, int wr, int wc, int fr, int fq) const {
;         const int row0 = u.pm * BM + wr * 64 + fr, col0 = wc * 32 + 8 * fq;
; #pragma unroll
;         for (int ai = 0; ai < 2; ++ai) {
;             f32x4 pa[4], pb[4];
; #pragma unroll
;             for (int m = 0; m < 4; ++m) { const f32x4* pp = (const f32x4*)(rowsq + (size_t)(row0 + ai * HALF + m * 16) * 32 + 8 * fq); pa[m] = pp[0]; pb[m] = pp[1]; }
; #pragma unroll
;             for (int m = 0; m < 4; ++m) { const int row = row0 + ai * HALF + m * 16; const f32x4 a = pa[m], b = pb[m];
;                 float sq = ((a[0] + a[1]) + (a[2] + a[3])) + ((b[0] + b[1]) + (b[2] + b[3])); sq += __shfl_xor(sq, 16); sq += __shfl_xor(sq, 32);
;                 const float rs = __builtin_amdgcn_rsqf(sq * inv_k + eps);
.LBB0_217:
	v_cmp_lt_i32_e32 vcc, v224, v219
	v_lshl_add_u32 v168, s36, 8, v176
	v_ashrrev_i32_e32 v169, 31, v168
	v_cndmask_b32_e32 v114, v218, v224, vcc
	v_cmp_lt_i32_e32 vcc, v225, v219
	v_lshlrev_b32_e32 v180, 2, v114
	v_or_b32_e32 v174, 16, v168
	v_cndmask_b32_e32 v114, v218, v225, vcc
	v_lshlrev_b32_e32 v179, 2, v114
	v_lshlrev_b64 v[114:115], 7, v[168:169]
	v_lshl_add_u64 v[114:115], v[162:163], 0, v[114:115]
	global_load_dwordx4 v[182:185], v[114:115], off
	global_load_dwordx4 v[186:189], v[114:115], off offset:16
	v_ashrrev_i32_e32 v175, 31, v174
	v_lshlrev_b64 v[114:115], 7, v[174:175]
	v_lshl_add_u64 v[114:115], v[162:163], 0, v[114:115]
	global_load_dwordx4 v[146:149], v[114:115], off
	global_load_dwordx4 v[150:153], v[114:115], off offset:16
	v_or_b32_e32 v172, 32, v168
	v_ashrrev_i32_e32 v173, 31, v172
	v_lshlrev_b64 v[114:115], 7, v[172:173]
	v_lshl_add_u64 v[114:115], v[162:163], 0, v[114:115]
	global_load_dwordx4 v[134:137], v[114:115], off
	global_load_dwordx4 v[130:133], v[114:115], off offset:16
	v_or_b32_e32 v170, 48, v168
	v_ashrrev_i32_e32 v171, 31, v170
	v_lshlrev_b64 v[114:115], 7, v[170:171]
	v_lshl_add_u64 v[114:115], v[162:163], 0, v[114:115]
	global_load_dwordx4 v[118:121], v[114:115], off
	s_nop 0
	global_load_dwordx4 v[114:117], v[114:115], off offset:16
	v_add_u32_e32 v250, 0x80, v168
	v_ashrrev_i32_e32 v251, 31, v250
	v_lshlrev_b64 v[250:251], 7, v[250:251]
	v_add_u32_e32 v252, 0xa0, v168
	v_ashrrev_i32_e32 v253, 31, v252
	v_lshlrev_b64 v[252:253], 7, v[252:253]
	v_lshl_add_u64 v[250:251], v[162:163], 0, v[250:251]
	v_lshl_add_u64 v[252:253], v[162:163], 0, v[252:253]
	global_load_dwordx4 v[192:195], v[250:251], off
	global_load_dwordx4 v[196:199], v[250:251], off offset:16
	global_load_dwordx4 v[200:203], v[250:251], off offset:2048
	global_load_dwordx4 v[208:211], v[250:251], off offset:2064
	global_load_dwordx4 v[230:233], v[252:253], off
	global_load_dwordx4 v[234:237], v[252:253], off offset:16
	global_load_dwordx4 v[242:245], v[252:253], off offset:2048
	global_load_dwordx4 v[246:249], v[252:253], off offset:2064
	s_lshl_b32 s14, s14, 1
	s_cmp_eq_u32 s27, 7
	s_cselect_b64 s[80:81], 0, -1
	s_cbranch_scc0 .Ltail_c
	s_lshr_b32 s15, s49, 7
	s_add_i32 s14, s14, s15
.Ltail_c:
	s_ashr_i32 s15, s14, 31
	s_lshl_b64 s[34:35], s[14:15], 14
	s_or_b32 s14, s14, 1
	s_ashr_i32 s15, s14, 31
	s_lshl_b64 s[36:37], s[14:15], 14
	s_andn2_b64 vcc, exec, s[38:39]
	s_waitcnt vmcnt(0)
	v_mov_b32_e32 v190, v182
	v_mov_b32_e32 v191, v186
	v_mov_b32_e32 v186, v183
	v_pk_add_f32 v[182:183], v[190:191], v[186:187]
	v_mov_b32_e32 v186, v184
	v_mov_b32_e32 v187, v188
	v_mov_b32_e32 v188, v185
	v_pk_add_f32 v[184:185], v[186:187], v[188:189]
	s_nop 0
	v_pk_add_f32 v[182:183], v[182:183], v[184:185]
	s_nop 0
	v_add_f32_e32 v181, v182, v183
	ds_bpermute_b32 v182, v180, v181
	s_waitcnt lgkmcnt(0)
	v_add_f32_e32 v181, v181, v182
	ds_bpermute_b32 v182, v179, v181
	s_waitcnt lgkmcnt(0)
	v_add_f32_e32 v181, v181, v182
	v_fmamk_f32 v181, v181, 0x3a000000, v215
	v_rsq_f32_e32 v182, v181
	s_nop 0
	v_pk_mul_f32 v[142:143], v[142:143], v[182:183] op_sel_hi:[1,0]
	v_pk_mul_f32 v[184:185], v[140:141], v[182:183] op_sel_hi:[1,0]
	v_pk_mul_f32 v[140:141], v[138:139], v[182:183] op_sel_hi:[1,0]
	v_cvt_pk_bf16_f32 v138, v142, v143
	v_lshl_add_u64 v[142:143], s[34:35], 0, v[168:169]
	v_lshlrev_b64 v[142:143], 8, v[142:143]
	v_pk_mul_f32 v[144:145], v[144:145], v[182:183] op_sel_hi:[1,0]
	v_lshl_add_u64 v[142:143], v[160:161], 0, v[142:143]
	v_cvt_pk_bf16_f32 v139, v144, v145
	v_pk_mul_f32 v[126:127], v[126:127], v[182:183] op_sel_hi:[1,0]
	v_cvt_pk_bf16_f32 v140, v140, v141
	v_cvt_pk_bf16_f32 v141, v184, v185
	global_store_dwordx4 v[142:143], v[138:141], off
	v_pk_mul_f32 v[128:129], v[128:129], v[182:183] op_sel_hi:[1,0]
	s_nop 0
	v_pk_mul_f32 v[138:139], v[124:125], v[182:183] op_sel_hi:[1,0]
	v_pk_mul_f32 v[124:125], v[122:123], v[182:183] op_sel_hi:[1,0]
	v_cvt_pk_bf16_f32 v122, v126, v127
	v_lshl_add_u64 v[126:127], s[36:37], 0, v[168:169]
	v_lshlrev_b64 v[126:127], 8, v[126:127]
	v_cvt_pk_bf16_f32 v123, v128, v129
	v_cvt_pk_bf16_f32 v124, v124, v125
	v_cvt_pk_bf16_f32 v125, v138, v139
	v_lshl_add_u64 v[126:127], v[160:161], 0, v[126:127]
	s_mov_b64 exec, s[80:81]
	global_store_dwordx4 v[126:127], v[122:125], off
	s_mov_b64 exec, -1
	s_nop 1
	v_mov_b32_e32 v122, v146
	v_mov_b32_e32 v123, v150
	v_mov_b32_e32 v150, v147
	v_mov_b32_e32 v124, v148
	v_mov_b32_e32 v125, v152
	v_mov_b32_e32 v152, v149
	v_pk_add_f32 v[122:123], v[122:123], v[150:151]
	v_pk_add_f32 v[124:125], v[124:125], v[152:153]
	s_nop 0
	v_pk_add_f32 v[122:123], v[122:123], v[124:125]
	s_nop 0
	v_add_f32_e32 v122, v122, v123
	ds_bpermute_b32 v123, v180, v122
	s_waitcnt lgkmcnt(0)
	v_add_f32_e32 v122, v122, v123
	ds_bpermute_b32 v123, v179, v122
	s_waitcnt lgkmcnt(0)
; __device__ __forceinline__ unsigned cvt_pk_bf16(float lo, float hi) { unsigned r; asm volatile("v_cvt_pk_bf16_f32 %0, %1, %2" : "=v"(r) : "v"(lo), "v"(hi)); return r; }
;     __device__ __forceinline__ void operator()(const f32x4 (&acc)[2][2][4][2], const Unit& u, int wr, int wc, int fr, int fq) const {
;         const int row0 = u.pm * BM + wr * 64 + fr, col0 = wc * 32 + 8 * fq;
; #pragma unroll
;         for (int ai = 0; ai < 2; ++ai) {
;             f32x4 pa[4], pb[4];
; #pragma unroll
;             for (int m = 0; m < 4; ++m) { const f32x4* pp = (const f32x4*)(rowsq + (size_t)(row0 + ai * HALF + m * 16) * 32 + 8 * fq); pa[m] = pp[0]; pb[m] = pp[1]; }
; #pragma unroll
;             for (int m = 0; m < 4; ++m) { const int row = row0 + ai * HALF + m * 16; const f32x4 a = pa[m], b = pb[m];
;                 float sq = ((a[0] + a[1]) + (a[2] + a[3])) + ((b[0] + b[1]) + (b[2] + b[3])); sq += __shfl_xor(sq, 16); sq += __shfl_xor(sq, 32);
;                 const float rs = __builtin_amdgcn_rsqf(sq * inv_k + eps);
; #pragma unroll
;                 for (int bj = 0; bj < 2; ++bj) { const f32x4 v0 = acc[ai][bj][m][0] * rs, v1 = acc[ai][bj][m][1] * rs;
;                     u32x4 w; w.x = cvt_pk_bf16(v0[0], v0[1]); w.y = cvt_pk_bf16(v0[2], v0[3]); w.z = cvt_pk_bf16(v1[0], v1[1]); w.w = cvt_pk_bf16(v1[2], v1[3]);
;                     *(u32x4*)(O + ((size_t)(u.pn * 2 + bj) * Mrows + row) * HALF + col0) = w; } }
;             asm volatile("" ::: "memory"); }
	v_add_f32_e32 v122, v122, v123
	v_fmamk_f32 v122, v122, 0x3a000000, v215
	v_rsq_f32_e32 v122, v122
	s_nop 0
	v_pk_mul_f32 v[110:111], v[110:111], v[122:123] op_sel_hi:[1,0]
	v_pk_mul_f32 v[124:125], v[108:109], v[122:123] op_sel_hi:[1,0]
	v_pk_mul_f32 v[108:109], v[106:107], v[122:123] op_sel_hi:[1,0]
	v_cvt_pk_bf16_f32 v106, v110, v111
	v_lshl_add_u64 v[110:111], s[34:35], 0, v[174:175]
	v_lshlrev_b64 v[110:111], 8, v[110:111]
	v_pk_mul_f32 v[112:113], v[112:113], v[122:123] op_sel_hi:[1,0]
	v_lshl_add_u64 v[110:111], v[160:161], 0, v[110:111]
	v_cvt_pk_bf16_f32 v107, v112, v113
	v_pk_mul_f32 v[102:103], v[102:103], v[122:123] op_sel_hi:[1,0]
	v_cvt_pk_bf16_f32 v108, v108, v109
	v_cvt_pk_bf16_f32 v109, v124, v125
	global_store_dwordx4 v[110:111], v[106:109], off
	v_pk_mul_f32 v[104:105], v[104:105], v[122:123] op_sel_hi:[1,0]
	s_nop 0
	v_pk_mul_f32 v[106:107], v[100:101], v[122:123] op_sel_hi:[1,0]
	v_pk_mul_f32 v[100:101], v[98:99], v[122:123] op_sel_hi:[1,0]
	v_cvt_pk_bf16_f32 v98, v102, v103
	v_lshl_add_u64 v[102:103], s[36:37], 0, v[174:175]
	v_lshlrev_b64 v[102:103], 8, v[102:103]
	v_cvt_pk_bf16_f32 v99, v104, v105
	v_cvt_pk_bf16_f32 v100, v100, v101
	v_cvt_pk_bf16_f32 v101, v106, v107
	v_lshl_add_u64 v[102:103], v[160:161], 0, v[102:103]
	s_mov_b64 exec, s[80:81]
	global_store_dwordx4 v[102:103], v[98:101], off
	s_mov_b64 exec, -1
	v_add_u32_e32 v104, 0x80, v168
	v_ashrrev_i32_e32 v105, 31, v104
	v_mov_b32_e32 v98, v134
	v_mov_b32_e32 v99, v130
	v_mov_b32_e32 v130, v135
	v_mov_b32_e32 v100, v136
	v_mov_b32_e32 v101, v132
	v_mov_b32_e32 v132, v137
	v_pk_add_f32 v[98:99], v[98:99], v[130:131]
	v_pk_add_f32 v[100:101], v[100:101], v[132:133]
	s_nop 0
	v_pk_add_f32 v[98:99], v[98:99], v[100:101]
	s_nop 0
	v_add_f32_e32 v98, v98, v99
	ds_bpermute_b32 v99, v180, v98
	s_waitcnt lgkmcnt(0)
	v_add_f32_e32 v98, v98, v99
	ds_bpermute_b32 v99, v179, v98
	s_waitcnt lgkmcnt(0)
	v_add_f32_e32 v98, v98, v99
	v_fmamk_f32 v98, v98, 0x3a000000, v215
	v_rsq_f32_e32 v98, v98
	s_nop 0
	v_pk_mul_f32 v[94:95], v[94:95], v[98:99] op_sel_hi:[1,0]
	v_pk_mul_f32 v[100:101], v[92:93], v[98:99] op_sel_hi:[1,0]
	v_pk_mul_f32 v[92:93], v[90:91], v[98:99] op_sel_hi:[1,0]
	v_cvt_pk_bf16_f32 v90, v94, v95
	v_lshl_add_u64 v[94:95], s[34:35], 0, v[172:173]
	v_lshlrev_b64 v[94:95], 8, v[94:95]
	v_pk_mul_f32 v[96:97], v[96:97], v[98:99] op_sel_hi:[1,0]
	v_lshl_add_u64 v[94:95], v[160:161], 0, v[94:95]
	v_cvt_pk_bf16_f32 v91, v96, v97
	v_pk_mul_f32 v[86:87], v[86:87], v[98:99] op_sel_hi:[1,0]
	v_cvt_pk_bf16_f32 v92, v92, v93
	v_cvt_pk_bf16_f32 v93, v100, v101
	global_store_dwordx4 v[94:95], v[90:93], off
	v_pk_mul_f32 v[88:89], v[88:89], v[98:99] op_sel_hi:[1,0]
	s_nop 0
	v_pk_mul_f32 v[90:91], v[84:85], v[98:99] op_sel_hi:[1,0]
	v_pk_mul_f32 v[84:85], v[82:83], v[98:99] op_sel_hi:[1,0]
	v_cvt_pk_bf16_f32 v82, v86, v87
	v_lshl_add_u64 v[86:87], s[36:37], 0, v[172:173]
	v_lshlrev_b64 v[86:87], 8, v[86:87]
	v_cvt_pk_bf16_f32 v83, v88, v89
	v_cvt_pk_bf16_f32 v84, v84, v85
	v_cvt_pk_bf16_f32 v85, v90, v91
	v_lshl_add_u64 v[86:87], v[160:161], 0, v[86:87]
	s_mov_b64 exec, s[80:81]
	global_store_dwordx4 v[86:87], v[82:85], off
	s_mov_b64 exec, -1
	v_add_u32_e32 v86, 0x90, v168
	v_ashrrev_i32_e32 v87, 31, v86
	v_mov_b32_e32 v82, v118
	v_mov_b32_e32 v83, v114
	v_mov_b32_e32 v114, v119
	v_mov_b32_e32 v84, v120
	v_mov_b32_e32 v85, v116
	v_mov_b32_e32 v116, v121
	v_pk_add_f32 v[82:83], v[82:83], v[114:115]
	v_pk_add_f32 v[84:85], v[84:85], v[116:117]
	s_nop 0
	v_pk_add_f32 v[82:83], v[82:83], v[84:85]
	s_nop 0
	v_add_f32_e32 v82, v82, v83
	ds_bpermute_b32 v83, v180, v82
	s_waitcnt lgkmcnt(0)
	v_add_f32_e32 v82, v82, v83
	ds_bpermute_b32 v83, v179, v82
	s_waitcnt lgkmcnt(0)
	v_add_f32_e32 v82, v82, v83
	v_fmamk_f32 v82, v82, 0x3a000000, v215
	v_rsq_f32_e32 v82, v82
	s_nop 0
	v_pk_mul_f32 v[78:79], v[78:79], v[82:83] op_sel_hi:[1,0]
	v_pk_mul_f32 v[84:85], v[76:77], v[82:83] op_sel_hi:[1,0]
	v_pk_mul_f32 v[76:77], v[74:75], v[82:83] op_sel_hi:[1,0]
	v_cvt_pk_bf16_f32 v74, v78, v79
	v_lshl_add_u64 v[78:79], s[34:35], 0, v[170:171]
	v_lshlrev_b64 v[78:79], 8, v[78:79]
	v_pk_mul_f32 v[80:81], v[80:81], v[82:83] op_sel_hi:[1,0]
	v_lshl_add_u64 v[78:79], v[160:161], 0, v[78:79]
	v_cvt_pk_bf16_f32 v75, v80, v81
	v_pk_mul_f32 v[70:71], v[70:71], v[82:83] op_sel_hi:[1,0]
	v_cvt_pk_bf16_f32 v76, v76, v77
	v_cvt_pk_bf16_f32 v77, v84, v85
	global_store_dwordx4 v[78:79], v[74:77], off
	v_pk_mul_f32 v[72:73], v[72:73], v[82:83] op_sel_hi:[1,0]
	v_add_u32_e32 v84, 0xa0, v168
	v_pk_mul_f32 v[74:75], v[68:69], v[82:83] op_sel_hi:[1,0]
	v_pk_mul_f32 v[68:69], v[66:67], v[82:83] op_sel_hi:[1,0]
	v_cvt_pk_bf16_f32 v66, v70, v71
	v_lshl_add_u64 v[70:71], s[36:37], 0, v[170:171]
	v_lshlrev_b64 v[70:71], 8, v[70:71]
	v_cvt_pk_bf16_f32 v67, v72, v73
	v_lshl_add_u64 v[70:71], v[160:161], 0, v[70:71]
	v_cvt_pk_bf16_f32 v68, v68, v69
	v_cvt_pk_bf16_f32 v69, v74, v75
	s_mov_b64 exec, s[80:81]
	global_store_dwordx4 v[70:71], v[66:69], off
	s_mov_b64 exec, -1
	v_ashrrev_i32_e32 v85, 31, v84
	v_add_u32_e32 v82, 0xb0, v168
	v_lshlrev_b64 v[66:67], 7, v[104:105]
	v_lshl_add_u64 v[66:67], v[162:163], 0, v[66:67]
	v_mov_b64_e32 v[88:89], v[192:193]
	v_mov_b64_e32 v[90:91], v[194:195]
	v_mov_b64_e32 v[92:93], v[196:197]
	v_mov_b64_e32 v[94:95], v[198:199]
	v_lshlrev_b64 v[66:67], 7, v[86:87]
	v_lshl_add_u64 v[66:67], v[162:163], 0, v[66:67]
	v_mov_b64_e32 v[96:97], v[200:201]
	v_mov_b64_e32 v[98:99], v[202:203]
	v_mov_b64_e32 v[100:101], v[208:209]
	v_mov_b64_e32 v[102:103], v[210:211]
	v_lshlrev_b64 v[66:67], 7, v[84:85]
	v_lshl_add_u64 v[66:67], v[162:163], 0, v[66:67]
	v_mov_b64_e32 v[78:79], v[230:231]
	v_mov_b64_e32 v[80:81], v[232:233]
	v_mov_b64_e32 v[74:75], v[234:235]
	v_mov_b64_e32 v[76:77], v[236:237]
	v_ashrrev_i32_e32 v83, 31, v82
	v_lshlrev_b64 v[66:67], 7, v[82:83]
	v_lshl_add_u64 v[66:67], v[162:163], 0, v[66:67]
	v_mov_b64_e32 v[70:71], v[242:243]
	v_mov_b64_e32 v[72:73], v[244:245]
	s_nop 0
	v_mov_b64_e32 v[66:67], v[246:247]
	v_mov_b64_e32 v[68:69], v[248:249]
	v_mov_b32_e32 v106, v88
	v_mov_b32_e32 v107, v92
	v_mov_b32_e32 v92, v89
	v_pk_add_f32 v[88:89], v[106:107], v[92:93]
	v_mov_b32_e32 v92, v90
	v_mov_b32_e32 v93, v94
	v_mov_b32_e32 v94, v91
	v_pk_add_f32 v[90:91], v[92:93], v[94:95]
	s_nop 0
	v_pk_add_f32 v[88:89], v[88:89], v[90:91]
	s_nop 0
	v_add_f32_e32 v88, v88, v89
	ds_bpermute_b32 v89, v180, v88
	s_waitcnt lgkmcnt(0)
; __device__ __forceinline__ unsigned cvt_pk_bf16(float lo, float hi) { unsigned r; asm volatile("v_cvt_pk_bf16_f32 %0, %1, %2" : "=v"(r) : "v"(lo), "v"(hi)); return r; }
;     __device__ __forceinline__ void operator()(const f32x4 (&acc)[2][2][4][2], const Unit& u, int wr, int wc, int fr, int fq) const {
;     ...
;             for (int m = 0; m < 4; ++m) { const int row = row0 + ai * HALF + m * 16; const f32x4 a = pa[m], b = pb[m];
;                 float sq = ((a[0] + a[1]) + (a[2] + a[3])) + ((b[0] + b[1]) + (b[2] + b[3])); sq += __shfl_xor(sq, 16); sq += __shfl_xor(sq, 32);
;                 const float rs = __builtin_amdgcn_rsqf(sq * inv_k + eps);
; #pragma unroll
;                 for (int bj = 0; bj < 2; ++bj) { const f32x4 v0 = acc[ai][bj][m][0] * rs, v1 = acc[ai][bj][m][1] * rs;
;                     u32x4 w; w.x = cvt_pk_bf16(v0[0], v0[1]); w.y = cvt_pk_bf16(v0[2], v0[3]); w.z = cvt_pk_bf16(v1[0], v1[1]); w.w = cvt_pk_bf16(v1[2], v1[3]);
;                     *(u32x4*)(O + ((size_t)(u.pn * 2 + bj) * Mrows + row) * HALF + col0) = w; } }
;             asm volatile("" ::: "memory"); }
	v_add_f32_e32 v88, v88, v89
	ds_bpermute_b32 v89, v179, v88
	s_waitcnt lgkmcnt(0)
	v_add_f32_e32 v88, v88, v89
	v_fmamk_f32 v88, v88, 0x3a000000, v215
	v_rsq_f32_e32 v88, v88
	s_nop 0
	v_pk_mul_f32 v[62:63], v[62:63], v[88:89] op_sel_hi:[1,0]
	v_pk_mul_f32 v[90:91], v[60:61], v[88:89] op_sel_hi:[1,0]
	v_pk_mul_f32 v[60:61], v[58:59], v[88:89] op_sel_hi:[1,0]
	v_cvt_pk_bf16_f32 v58, v62, v63
	v_lshl_add_u64 v[62:63], s[34:35], 0, v[104:105]
	v_lshlrev_b64 v[62:63], 8, v[62:63]
	v_pk_mul_f32 v[64:65], v[64:65], v[88:89] op_sel_hi:[1,0]
	v_lshl_add_u64 v[62:63], v[160:161], 0, v[62:63]
	v_cvt_pk_bf16_f32 v59, v64, v65
	v_pk_mul_f32 v[54:55], v[54:55], v[88:89] op_sel_hi:[1,0]
	v_cvt_pk_bf16_f32 v60, v60, v61
	v_cvt_pk_bf16_f32 v61, v90, v91
	global_store_dwordx4 v[62:63], v[58:61], off
	v_pk_mul_f32 v[56:57], v[56:57], v[88:89] op_sel_hi:[1,0]
	s_nop 0
	v_pk_mul_f32 v[58:59], v[52:53], v[88:89] op_sel_hi:[1,0]
	v_pk_mul_f32 v[52:53], v[50:51], v[88:89] op_sel_hi:[1,0]
	v_cvt_pk_bf16_f32 v50, v54, v55
	v_lshl_add_u64 v[54:55], s[36:37], 0, v[104:105]
	v_lshlrev_b64 v[54:55], 8, v[54:55]
	v_cvt_pk_bf16_f32 v51, v56, v57
	v_cvt_pk_bf16_f32 v52, v52, v53
	v_cvt_pk_bf16_f32 v53, v58, v59
	v_lshl_add_u64 v[54:55], v[160:161], 0, v[54:55]
	s_mov_b64 exec, s[80:81]
	global_store_dwordx4 v[54:55], v[50:53], off
	s_mov_b64 exec, -1
	s_nop 0
	v_mov_b32_e32 v50, v96
	v_mov_b32_e32 v51, v100
	v_mov_b32_e32 v100, v97
	v_mov_b32_e32 v52, v98
	v_mov_b32_e32 v53, v102
	v_mov_b32_e32 v102, v99
	v_pk_add_f32 v[50:51], v[50:51], v[100:101]
	v_pk_add_f32 v[52:53], v[52:53], v[102:103]
	s_nop 0
	v_pk_add_f32 v[50:51], v[50:51], v[52:53]
	s_nop 0
	v_add_f32_e32 v50, v50, v51
	ds_bpermute_b32 v51, v180, v50
	s_waitcnt lgkmcnt(0)
	v_add_f32_e32 v50, v50, v51
	ds_bpermute_b32 v51, v179, v50
	s_waitcnt lgkmcnt(0)
	v_add_f32_e32 v50, v50, v51
	v_fmamk_f32 v50, v50, 0x3a000000, v215
	v_rsq_f32_e32 v50, v50
	s_nop 0
	v_pk_mul_f32 v[46:47], v[46:47], v[50:51] op_sel_hi:[1,0]
	v_pk_mul_f32 v[52:53], v[44:45], v[50:51] op_sel_hi:[1,0]
	v_pk_mul_f32 v[44:45], v[42:43], v[50:51] op_sel_hi:[1,0]
	v_cvt_pk_bf16_f32 v42, v46, v47
	v_lshl_add_u64 v[46:47], s[34:35], 0, v[86:87]
	v_lshlrev_b64 v[46:47], 8, v[46:47]
	v_pk_mul_f32 v[48:49], v[48:49], v[50:51] op_sel_hi:[1,0]
	v_lshl_add_u64 v[46:47], v[160:161], 0, v[46:47]
	v_cvt_pk_bf16_f32 v43, v48, v49
	v_pk_mul_f32 v[38:39], v[38:39], v[50:51] op_sel_hi:[1,0]
	v_cvt_pk_bf16_f32 v44, v44, v45
	v_cvt_pk_bf16_f32 v45, v52, v53
	global_store_dwordx4 v[46:47], v[42:45], off
	v_pk_mul_f32 v[40:41], v[40:41], v[50:51] op_sel_hi:[1,0]
	s_nop 0
	v_pk_mul_f32 v[42:43], v[36:37], v[50:51] op_sel_hi:[1,0]
	v_pk_mul_f32 v[36:37], v[34:35], v[50:51] op_sel_hi:[1,0]
	v_cvt_pk_bf16_f32 v34, v38, v39
	v_lshl_add_u64 v[38:39], s[36:37], 0, v[86:87]
	v_lshlrev_b64 v[38:39], 8, v[38:39]
	v_cvt_pk_bf16_f32 v35, v40, v41
	v_cvt_pk_bf16_f32 v36, v36, v37
	v_cvt_pk_bf16_f32 v37, v42, v43
	v_lshl_add_u64 v[38:39], v[160:161], 0, v[38:39]
	s_mov_b64 exec, s[80:81]
	global_store_dwordx4 v[38:39], v[34:37], off
	s_mov_b64 exec, -1
	s_nop 0
	v_mov_b32_e32 v34, v78
	v_mov_b32_e32 v35, v74
	v_mov_b32_e32 v74, v79
	v_mov_b32_e32 v36, v80
	v_mov_b32_e32 v37, v76
	v_mov_b32_e32 v76, v81
	v_pk_add_f32 v[34:35], v[34:35], v[74:75]
	v_pk_add_f32 v[36:37], v[36:37], v[76:77]
	s_nop 0
	v_pk_add_f32 v[34:35], v[34:35], v[36:37]
	s_nop 0
	v_add_f32_e32 v34, v34, v35
	ds_bpermute_b32 v35, v180, v34
	s_waitcnt lgkmcnt(0)
	v_add_f32_e32 v34, v34, v35
	ds_bpermute_b32 v35, v179, v34
	s_waitcnt lgkmcnt(0)
	v_add_f32_e32 v34, v34, v35
	v_fmamk_f32 v34, v34, 0x3a000000, v215
	v_rsq_f32_e32 v34, v34
	s_nop 0
	v_pk_mul_f32 v[30:31], v[30:31], v[34:35] op_sel_hi:[1,0]
	v_pk_mul_f32 v[36:37], v[28:29], v[34:35] op_sel_hi:[1,0]
	v_pk_mul_f32 v[28:29], v[26:27], v[34:35] op_sel_hi:[1,0]
	v_cvt_pk_bf16_f32 v26, v30, v31
	v_lshl_add_u64 v[30:31], s[34:35], 0, v[84:85]
	v_lshlrev_b64 v[30:31], 8, v[30:31]
	v_pk_mul_f32 v[32:33], v[32:33], v[34:35] op_sel_hi:[1,0]
	v_lshl_add_u64 v[30:31], v[160:161], 0, v[30:31]
	v_cvt_pk_bf16_f32 v27, v32, v33
	v_pk_mul_f32 v[22:23], v[22:23], v[34:35] op_sel_hi:[1,0]
	v_cvt_pk_bf16_f32 v28, v28, v29
	v_cvt_pk_bf16_f32 v29, v36, v37
	global_store_dwordx4 v[30:31], v[26:29], off
	v_pk_mul_f32 v[24:25], v[24:25], v[34:35] op_sel_hi:[1,0]
	s_nop 0
	v_pk_mul_f32 v[26:27], v[20:21], v[34:35] op_sel_hi:[1,0]
	v_pk_mul_f32 v[20:21], v[18:19], v[34:35] op_sel_hi:[1,0]
	v_cvt_pk_bf16_f32 v18, v22, v23
	v_lshl_add_u64 v[22:23], s[36:37], 0, v[84:85]
	v_lshlrev_b64 v[22:23], 8, v[22:23]
	v_cvt_pk_bf16_f32 v19, v24, v25
	v_cvt_pk_bf16_f32 v20, v20, v21
	v_cvt_pk_bf16_f32 v21, v26, v27
	v_lshl_add_u64 v[22:23], v[160:161], 0, v[22:23]
	s_mov_b64 exec, s[80:81]
	global_store_dwordx4 v[22:23], v[18:21], off
	s_mov_b64 exec, -1
	s_nop 0
	v_mov_b32_e32 v18, v70
	v_mov_b32_e32 v19, v66
	v_mov_b32_e32 v66, v71
	v_mov_b32_e32 v20, v72
	v_mov_b32_e32 v21, v68
	v_mov_b32_e32 v68, v73
	v_pk_add_f32 v[18:19], v[18:19], v[66:67]
	v_pk_add_f32 v[20:21], v[20:21], v[68:69]
	s_nop 0
	v_pk_add_f32 v[18:19], v[18:19], v[20:21]
	s_nop 0
	v_add_f32_e32 v18, v18, v19
	ds_bpermute_b32 v19, v180, v18
	s_waitcnt lgkmcnt(0)
	v_add_f32_e32 v18, v18, v19
	ds_bpermute_b32 v19, v179, v18
	s_waitcnt lgkmcnt(0)
	v_add_f32_e32 v18, v18, v19
	v_fmamk_f32 v18, v18, 0x3a000000, v215
	v_rsq_f32_e32 v18, v18
	s_nop 0
	v_pk_mul_f32 v[14:15], v[14:15], v[18:19] op_sel_hi:[1,0]
	v_pk_mul_f32 v[20:21], v[12:13], v[18:19] op_sel_hi:[1,0]
	v_pk_mul_f32 v[12:13], v[10:11], v[18:19] op_sel_hi:[1,0]
	v_cvt_pk_bf16_f32 v10, v14, v15
	v_lshl_add_u64 v[14:15], s[34:35], 0, v[82:83]
	v_lshlrev_b64 v[14:15], 8, v[14:15]
	v_pk_mul_f32 v[16:17], v[16:17], v[18:19] op_sel_hi:[1,0]
	v_lshl_add_u64 v[14:15], v[160:161], 0, v[14:15]
	v_cvt_pk_bf16_f32 v11, v16, v17
	v_pk_mul_f32 v[6:7], v[6:7], v[18:19] op_sel_hi:[1,0]
	v_cvt_pk_bf16_f32 v12, v12, v13
	v_cvt_pk_bf16_f32 v13, v20, v21
	global_store_dwordx4 v[14:15], v[10:13], off
	v_pk_mul_f32 v[8:9], v[8:9], v[18:19] op_sel_hi:[1,0]
	s_mov_b64 s[34:35], -1
	v_pk_mul_f32 v[10:11], v[4:5], v[18:19] op_sel_hi:[1,0]
	v_pk_mul_f32 v[4:5], v[2:3], v[18:19] op_sel_hi:[1,0]
	v_cvt_pk_bf16_f32 v2, v6, v7
	v_lshl_add_u64 v[6:7], s[36:37], 0, v[82:83]
	v_lshlrev_b64 v[6:7], 8, v[6:7]
	v_lshl_add_u64 v[6:7], v[160:161], 0, v[6:7]
	v_cvt_pk_bf16_f32 v3, v8, v9
	v_cvt_pk_bf16_f32 v4, v4, v5
	v_cvt_pk_bf16_f32 v5, v10, v11
	s_mov_b64 exec, s[80:81]
	global_store_dwordx4 v[6:7], v[2:5], off
	s_mov_b64 exec, -1
	s_cbranch_vccnz .LBB0_210
	s_andn2_b64 vcc, exec, s[0:1]
	s_cbranch_vccnz .LBB0_209
	s_barrier
	s_branch .LBB0_209
